# prep w_in transposes hand-written: 4-deep prefetch, rotating LDS buffers, 1 barrier/tile
# baseline (speedup 1.0000x reference)
; __device__ __forceinline__ unsigned pack2(float a, float b){ f32x2_t v={a,b}; bf16x2_t r=__builtin_convertvector(v,bf16x2_t); return __builtin_bit_cast(unsigned,r); }
; __device__ __forceinline__ void transpose_tile(const float* __restrict__ src, int ld_src, int kind, u16* __restrict__ dst, int n0, int k0, int tid){
;   float* tile = (float*)smem;
;   _Pragma("unroll") for (int i=0;i<2;++i){ int e=tid+512*i; int kk=e>>4, n4=(e&15)*4; int np=n0+n4;
;     float4 v=make_float4(0.f,0.f,0.f,0.f);
;     if (kind==0){ int ns=wperm(np);
;       if (ns>=0) v=*(const float4*)(src+(size_t)(k0+kk)*ld_src+ns); }
;     else v=*(const float4*)(src+(size_t)(k0+kk)*ld_src+np);
;     *(float4*)(tile+kk*68+n4)=v; }
;   __syncthreads();
;   { int nn=tid>>3, k8=(tid&7)*8;
;     u32x4 pk;
;     pk[0]=pack2(tile[(k8+0)*68+nn],tile[(k8+1)*68+nn]); pk[1]=pack2(tile[(k8+2)*68+nn],tile[(k8+3)*68+nn]);
;     pk[2]=pack2(tile[(k8+4)*68+nn],tile[(k8+5)*68+nn]); pk[3]=pack2(tile[(k8+6)*68+nn],tile[(k8+7)*68+nn]);
;     *(u32x4*)(dst+(size_t)(n0+nn)*1024+k0+k8)=pk; }
;   __syncthreads();
; }
; __device__ __forceinline__ void phase_prep(KP kp_){ asm volatile("" : "+s"(kp_)); const Params p=load_params(kp_);
;   int ftid=threadIdx.x; asm volatile("" : "+v"(ftid));
;   int tid=ftid, lane=tid&63, wid=tid>>6;
;   char* ws=p.ws;
;   for (int it=blockIdx.x; it<2624; it+=gridDim.x){
;     { int nt_=it>>4, kt=it&15; transpose_tile(p.w_in,10272,0,(u16*)(ws+OFF_WTIN),nt_*64,kt*64,tid); }
.LBB0_8:
	v_readlane_b32 s10, v253, 12
	v_readlane_b32 s11, v253, 13
	s_load_dwordx2 s[46:47], s[10:11], 0x8
	s_load_dwordx4 s[48:51], s[10:11], 0x18
	s_load_dwordx2 s[6:7], s[10:11], 0x28
	s_load_dwordx2 s[8:9], s[10:11], 0xe0
	v_mov_b32_e32 v8, v154
	s_andn2_b64 vcc, exec, s[54:55]
	v_add_u32_e32 v12, 0x200, v8
	s_cbranch_vccnz .LBB0_13
	s_load_dwordx2 s[42:43], s[10:11], 0x38
	v_readlane_b32 s14, v253, 6
	v_lshrrev_b32_e32 v50, 4, v154
	v_and_b32_e32 v51, 15, v154
	v_lshlrev_b32_e32 v51, 2, v51
	s_and_b32 s15, s14, 15
	s_lshl_b32 s15, s15, 6
	s_lshr_b32 s44, s14, 4
	v_add_u32_e32 v56, s15, v50
	s_mov_b32 s45, 0xa080
	v_mul_lo_u32 v52, v56, s45
	v_lshl_add_u32 v52, v51, 2, v52
	v_mul_u32_u24_e32 v53, 0x110, v50
	v_lshl_add_u32 v53, v51, 2, v53
	v_and_b32_e32 v56, 7, v154
	v_mul_u32_u24_e32 v54, 0x880, v56
	v_lshrrev_b32_e32 v55, 3, v154
	v_lshl_add_u32 v54, v55, 2, v54
	v_lshlrev_b32_e32 v55, 11, v55
	v_lshl_add_u32 v55, v56, 4, v55
	s_waitcnt lgkmcnt(0)
	s_lshl_b32 s12, s44, 17
	s_lshl_b32 s13, s15, 1
	s_add_u32 s12, s12, s13
	s_add_u32 s12, s8, s12
	s_addc_u32 s13, s9, 0
	s_lshl_b32 s44, s44, 6
	s_mov_b32 s10, s44
	s_add_u32 s11, s10, 32
	s_cmp_lt_u32 s10, 0x1000
	s_cselect_b32 s10, s10, s11
	s_lshl_b32 s10, s10, 2
	s_add_u32 s10, s42, s10
	s_addc_u32 s11, s43, 0
	global_load_dwordx4 v[60:63], v52, s[10:11]
	s_add_u32 s10, s10, 0x141000
	s_addc_u32 s11, s11, 0
	global_load_dwordx4 v[64:67], v52, s[10:11]
	s_add_u32 s10, s44, 0x400
	s_add_u32 s11, s10, 32
	s_cmp_lt_u32 s10, 0x1000
	s_cselect_b32 s10, s10, s11
	s_lshl_b32 s10, s10, 2
	s_add_u32 s10, s42, s10
	s_addc_u32 s11, s43, 0
	global_load_dwordx4 v[68:71], v52, s[10:11]
	s_add_u32 s10, s10, 0x141000
	s_addc_u32 s11, s11, 0
	global_load_dwordx4 v[72:75], v52, s[10:11]
	s_add_u32 s10, s44, 0x800
	s_add_u32 s11, s10, 32
	s_cmp_lt_u32 s10, 0x1000
	s_cselect_b32 s10, s10, s11
	s_lshl_b32 s10, s10, 2
	s_add_u32 s10, s42, s10
	s_addc_u32 s11, s43, 0
	global_load_dwordx4 v[76:79], v52, s[10:11]
	s_add_u32 s10, s10, 0x141000
	s_addc_u32 s11, s11, 0
	global_load_dwordx4 v[80:83], v52, s[10:11]
	s_add_u32 s10, s44, 0xc00
	s_add_u32 s11, s10, 32
	s_cmp_lt_u32 s10, 0x1000
	s_cselect_b32 s10, s10, s11
	s_lshl_b32 s10, s10, 2
	s_add_u32 s10, s42, s10
	s_addc_u32 s11, s43, 0
	global_load_dwordx4 v[84:87], v52, s[10:11]
	s_add_u32 s10, s10, 0x141000
	s_addc_u32 s11, s11, 0
	global_load_dwordx4 v[88:91], v52, s[10:11]
	s_barrier
	s_waitcnt vmcnt(6)
	ds_write_b128 v53, v[60:63] offset:0
	ds_write_b128 v53, v[64:67] offset:8704
	s_waitcnt lgkmcnt(0)
	s_barrier
	ds_read_b32 v96, v54 offset:0
	ds_read_b32 v97, v54 offset:272
	ds_read_b32 v98, v54 offset:544
	ds_read_b32 v99, v54 offset:816
	ds_read_b32 v100, v54 offset:1088
	ds_read_b32 v101, v54 offset:1360
	ds_read_b32 v102, v54 offset:1632
	ds_read_b32 v103, v54 offset:1904
	s_add_u32 s10, s44, 0x1000
	s_add_u32 s11, s10, 32
	s_cmp_lt_u32 s10, 0x1000
	s_cselect_b32 s10, s10, s11
	s_lshl_b32 s10, s10, 2
	s_add_u32 s10, s42, s10
	s_addc_u32 s11, s43, 0
	global_load_dwordx4 v[60:63], v52, s[10:11]
	s_add_u32 s10, s10, 0x141000
	s_addc_u32 s11, s11, 0
	global_load_dwordx4 v[64:67], v52, s[10:11]
	s_waitcnt lgkmcnt(0)
	v_cvt_pk_bf16_f32 v104, v96, v97
	v_cvt_pk_bf16_f32 v105, v98, v99
	v_cvt_pk_bf16_f32 v106, v100, v101
	v_cvt_pk_bf16_f32 v107, v102, v103
	global_store_dwordx4 v55, v[104:107], s[12:13]
	s_nop 1
	s_waitcnt vmcnt(7)
	ds_write_b128 v53, v[68:71] offset:17408
	ds_write_b128 v53, v[72:75] offset:26112
	s_waitcnt lgkmcnt(0)
	s_barrier
	ds_read_b32 v96, v54 offset:17408
	ds_read_b32 v97, v54 offset:17680
	ds_read_b32 v98, v54 offset:17952
	ds_read_b32 v99, v54 offset:18224
	ds_read_b32 v100, v54 offset:18496
	ds_read_b32 v101, v54 offset:18768
	ds_read_b32 v102, v54 offset:19040
	ds_read_b32 v103, v54 offset:19312
	s_add_u32 s10, s44, 0x1400
	s_add_u32 s11, s10, 32
	s_cmp_lt_u32 s10, 0x1000
	s_cselect_b32 s10, s10, s11
	s_lshl_b32 s10, s10, 2
	s_add_u32 s10, s42, s10
	s_addc_u32 s11, s43, 0
	global_load_dwordx4 v[68:71], v52, s[10:11]
	s_add_u32 s10, s10, 0x141000
	s_addc_u32 s11, s11, 0
	global_load_dwordx4 v[72:75], v52, s[10:11]
	s_waitcnt lgkmcnt(0)
	v_cvt_pk_bf16_f32 v104, v96, v97
	v_cvt_pk_bf16_f32 v105, v98, v99
	v_cvt_pk_bf16_f32 v106, v100, v101
	v_cvt_pk_bf16_f32 v107, v102, v103
	s_add_u32 s10, s12, 0x200000
	s_addc_u32 s11, s13, 0
	global_store_dwordx4 v55, v[104:107], s[10:11]
	s_nop 1
	s_waitcnt vmcnt(8)
	ds_write_b128 v53, v[76:79] offset:34816
	ds_write_b128 v53, v[80:83] offset:43520
	s_waitcnt lgkmcnt(0)
	s_barrier
	ds_read_b32 v96, v54 offset:34816
	ds_read_b32 v97, v54 offset:35088
	ds_read_b32 v98, v54 offset:35360
	ds_read_b32 v99, v54 offset:35632
	ds_read_b32 v100, v54 offset:35904
	ds_read_b32 v101, v54 offset:36176
	ds_read_b32 v102, v54 offset:36448
	ds_read_b32 v103, v54 offset:36720
	s_add_u32 s10, s44, 0x1800
	s_add_u32 s11, s10, 32
	s_cmp_lt_u32 s10, 0x1000
	s_cselect_b32 s10, s10, s11
	s_lshl_b32 s10, s10, 2
	s_add_u32 s10, s42, s10
	s_addc_u32 s11, s43, 0
	global_load_dwordx4 v[76:79], v52, s[10:11]
	s_add_u32 s10, s10, 0x141000
	s_addc_u32 s11, s11, 0
	global_load_dwordx4 v[80:83], v52, s[10:11]
	s_waitcnt lgkmcnt(0)
	v_cvt_pk_bf16_f32 v104, v96, v97
	v_cvt_pk_bf16_f32 v105, v98, v99
	v_cvt_pk_bf16_f32 v106, v100, v101
	v_cvt_pk_bf16_f32 v107, v102, v103
	s_add_u32 s10, s12, 0x400000
	s_addc_u32 s11, s13, 0
	global_store_dwordx4 v55, v[104:107], s[10:11]
	s_nop 1
	s_waitcnt vmcnt(9)
	ds_write_b128 v53, v[84:87] offset:52224
	ds_write_b128 v53, v[88:91] offset:60928
	s_waitcnt lgkmcnt(0)
	s_barrier
; __device__ __forceinline__ unsigned pack2(float a, float b){ f32x2_t v={a,b}; bf16x2_t r=__builtin_convertvector(v,bf16x2_t); return __builtin_bit_cast(unsigned,r); }
; __device__ __forceinline__ void transpose_tile(const float* __restrict__ src, int ld_src, int kind, u16* __restrict__ dst, int n0, int k0, int tid){
;     ...
;   _Pragma("unroll") for (int i=0;i<2;++i){ int e=tid+512*i; int kk=e>>4, n4=(e&15)*4; int np=n0+n4;
;     float4 v=make_float4(0.f,0.f,0.f,0.f);
;     if (kind==0){ int ns=wperm(np);
;       if (ns>=0) v=*(const float4*)(src+(size_t)(k0+kk)*ld_src+ns); }
;     else v=*(const float4*)(src+(size_t)(k0+kk)*ld_src+np);
;     *(float4*)(tile+kk*68+n4)=v; }
;   __syncthreads();
;   { int nn=tid>>3, k8=(tid&7)*8;
;     u32x4 pk;
;     pk[0]=pack2(tile[(k8+0)*68+nn],tile[(k8+1)*68+nn]); pk[1]=pack2(tile[(k8+2)*68+nn],tile[(k8+3)*68+nn]);
;     pk[2]=pack2(tile[(k8+4)*68+nn],tile[(k8+5)*68+nn]); pk[3]=pack2(tile[(k8+6)*68+nn],tile[(k8+7)*68+nn]);
;     *(u32x4*)(dst+(size_t)(n0+nn)*1024+k0+k8)=pk; }
;   __syncthreads();
	ds_read_b32 v96, v54 offset:52224
	ds_read_b32 v97, v54 offset:52496
	ds_read_b32 v98, v54 offset:52768
	ds_read_b32 v99, v54 offset:53040
	ds_read_b32 v100, v54 offset:53312
	ds_read_b32 v101, v54 offset:53584
	ds_read_b32 v102, v54 offset:53856
	ds_read_b32 v103, v54 offset:54128
	s_add_u32 s10, s44, 0x1c00
	s_add_u32 s11, s10, 32
	s_cmp_lt_u32 s10, 0x1000
	s_cselect_b32 s10, s10, s11
	s_lshl_b32 s10, s10, 2
	s_add_u32 s10, s42, s10
	s_addc_u32 s11, s43, 0
	global_load_dwordx4 v[84:87], v52, s[10:11]
	s_add_u32 s10, s10, 0x141000
	s_addc_u32 s11, s11, 0
	global_load_dwordx4 v[88:91], v52, s[10:11]
	s_waitcnt lgkmcnt(0)
	v_cvt_pk_bf16_f32 v104, v96, v97
	v_cvt_pk_bf16_f32 v105, v98, v99
	v_cvt_pk_bf16_f32 v106, v100, v101
	v_cvt_pk_bf16_f32 v107, v102, v103
	s_add_u32 s10, s12, 0x600000
	s_addc_u32 s11, s13, 0
	global_store_dwordx4 v55, v[104:107], s[10:11]
	s_nop 1
	s_waitcnt vmcnt(10)
	ds_write_b128 v53, v[60:63] offset:0
	ds_write_b128 v53, v[64:67] offset:8704
	s_waitcnt lgkmcnt(0)
	s_barrier
	ds_read_b32 v96, v54 offset:0
	ds_read_b32 v97, v54 offset:272
	ds_read_b32 v98, v54 offset:544
	ds_read_b32 v99, v54 offset:816
	ds_read_b32 v100, v54 offset:1088
	ds_read_b32 v101, v54 offset:1360
	ds_read_b32 v102, v54 offset:1632
	ds_read_b32 v103, v54 offset:1904
	s_add_u32 s10, s44, 0x2000
	s_add_u32 s11, s10, 32
	s_cmp_lt_u32 s10, 0x1000
	s_cselect_b32 s10, s10, s11
	s_lshl_b32 s10, s10, 2
	s_add_u32 s10, s42, s10
	s_addc_u32 s11, s43, 0
	global_load_dwordx4 v[60:63], v52, s[10:11]
	s_add_u32 s10, s10, 0x141000
	s_addc_u32 s11, s11, 0
	global_load_dwordx4 v[64:67], v52, s[10:11]
	s_waitcnt lgkmcnt(0)
	v_cvt_pk_bf16_f32 v104, v96, v97
	v_cvt_pk_bf16_f32 v105, v98, v99
	v_cvt_pk_bf16_f32 v106, v100, v101
	v_cvt_pk_bf16_f32 v107, v102, v103
	s_add_u32 s10, s12, 0x800000
	s_addc_u32 s11, s13, 0
	global_store_dwordx4 v55, v[104:107], s[10:11]
	s_nop 1
	s_waitcnt vmcnt(10)
	ds_write_b128 v53, v[68:71] offset:17408
	ds_write_b128 v53, v[72:75] offset:26112
	s_waitcnt lgkmcnt(0)
	s_barrier
	ds_read_b32 v96, v54 offset:17408
	ds_read_b32 v97, v54 offset:17680
	ds_read_b32 v98, v54 offset:17952
	ds_read_b32 v99, v54 offset:18224
	ds_read_b32 v100, v54 offset:18496
	ds_read_b32 v101, v54 offset:18768
	ds_read_b32 v102, v54 offset:19040
	ds_read_b32 v103, v54 offset:19312
	s_add_u32 s10, s44, 0x2400
	s_add_u32 s11, s10, 32
	s_cmp_lt_u32 s10, 0x1000
	s_cselect_b32 s10, s10, s11
	s_lshl_b32 s10, s10, 2
	s_add_u32 s10, s42, s10
	s_addc_u32 s11, s43, 0
	global_load_dwordx4 v[68:71], v52, s[10:11]
	s_add_u32 s10, s10, 0x141000
	s_addc_u32 s11, s11, 0
	global_load_dwordx4 v[72:75], v52, s[10:11]
	s_waitcnt lgkmcnt(0)
	v_cvt_pk_bf16_f32 v104, v96, v97
	v_cvt_pk_bf16_f32 v105, v98, v99
	v_cvt_pk_bf16_f32 v106, v100, v101
	v_cvt_pk_bf16_f32 v107, v102, v103
	s_add_u32 s10, s12, 0xa00000
	s_addc_u32 s11, s13, 0
	global_store_dwordx4 v55, v[104:107], s[10:11]
	s_nop 1
	s_waitcnt vmcnt(10)
	ds_write_b128 v53, v[76:79] offset:34816
	ds_write_b128 v53, v[80:83] offset:43520
	s_waitcnt lgkmcnt(0)
	s_barrier
	ds_read_b32 v96, v54 offset:34816
	ds_read_b32 v97, v54 offset:35088
	ds_read_b32 v98, v54 offset:35360
	ds_read_b32 v99, v54 offset:35632
	ds_read_b32 v100, v54 offset:35904
	ds_read_b32 v101, v54 offset:36176
	ds_read_b32 v102, v54 offset:36448
	ds_read_b32 v103, v54 offset:36720
	s_add_u32 s10, s44, 0x2800
	s_mov_b32 s10, 0x1000
	s_lshl_b32 s10, s10, 2
	s_add_u32 s10, s42, s10
	s_addc_u32 s11, s43, 0
	global_load_dwordx4 v[76:79], v52, s[10:11]
	s_add_u32 s10, s10, 0x141000
	s_addc_u32 s11, s11, 0
	global_load_dwordx4 v[80:83], v52, s[10:11]
	s_waitcnt lgkmcnt(0)
	v_cvt_pk_bf16_f32 v104, v96, v97
	v_cvt_pk_bf16_f32 v105, v98, v99
	v_cvt_pk_bf16_f32 v106, v100, v101
	v_cvt_pk_bf16_f32 v107, v102, v103
	s_add_u32 s10, s12, 0xc00000
	s_addc_u32 s11, s13, 0
	global_store_dwordx4 v55, v[104:107], s[10:11]
	s_nop 1
	s_waitcnt vmcnt(10)
	ds_write_b128 v53, v[84:87] offset:52224
	ds_write_b128 v53, v[88:91] offset:60928
	s_waitcnt lgkmcnt(0)
	s_barrier
	ds_read_b32 v96, v54 offset:52224
	ds_read_b32 v97, v54 offset:52496
	ds_read_b32 v98, v54 offset:52768
	ds_read_b32 v99, v54 offset:53040
	ds_read_b32 v100, v54 offset:53312
	ds_read_b32 v101, v54 offset:53584
	ds_read_b32 v102, v54 offset:53856
	ds_read_b32 v103, v54 offset:54128
	s_waitcnt lgkmcnt(0)
	v_cvt_pk_bf16_f32 v104, v96, v97
	v_cvt_pk_bf16_f32 v105, v98, v99
	v_cvt_pk_bf16_f32 v106, v100, v101
	v_cvt_pk_bf16_f32 v107, v102, v103
	s_add_u32 s10, s12, 0xe00000
	s_addc_u32 s11, s13, 0
	global_store_dwordx4 v55, v[104:107], s[10:11]
	s_nop 1
	s_waitcnt vmcnt(8)
	ds_write_b128 v53, v[60:63] offset:0
	ds_write_b128 v53, v[64:67] offset:8704
	s_waitcnt lgkmcnt(0)
	s_barrier
	ds_read_b32 v96, v54 offset:0
	ds_read_b32 v97, v54 offset:272
	ds_read_b32 v98, v54 offset:544
	ds_read_b32 v99, v54 offset:816
	ds_read_b32 v100, v54 offset:1088
	ds_read_b32 v101, v54 offset:1360
	ds_read_b32 v102, v54 offset:1632
	ds_read_b32 v103, v54 offset:1904
	s_waitcnt lgkmcnt(0)
	v_cvt_pk_bf16_f32 v104, v96, v97
	v_cvt_pk_bf16_f32 v105, v98, v99
	v_cvt_pk_bf16_f32 v106, v100, v101
	v_cvt_pk_bf16_f32 v107, v102, v103
	s_add_u32 s10, s12, 0x1000000
	s_addc_u32 s11, s13, 0
	global_store_dwordx4 v55, v[104:107], s[10:11]
	s_nop 1
	s_waitcnt vmcnt(6)
	ds_write_b128 v53, v[68:71] offset:17408
	ds_write_b128 v53, v[72:75] offset:26112
	s_waitcnt lgkmcnt(0)
	s_barrier
	ds_read_b32 v96, v54 offset:17408
	ds_read_b32 v97, v54 offset:17680
	ds_read_b32 v98, v54 offset:17952
	ds_read_b32 v99, v54 offset:18224
	ds_read_b32 v100, v54 offset:18496
	ds_read_b32 v101, v54 offset:18768
	ds_read_b32 v102, v54 offset:19040
	ds_read_b32 v103, v54 offset:19312
	s_waitcnt lgkmcnt(0)
	v_cvt_pk_bf16_f32 v104, v96, v97
	v_cvt_pk_bf16_f32 v105, v98, v99
	v_cvt_pk_bf16_f32 v106, v100, v101
	v_cvt_pk_bf16_f32 v107, v102, v103
	s_add_u32 s10, s12, 0x1200000
	s_addc_u32 s11, s13, 0
	global_store_dwordx4 v55, v[104:107], s[10:11]
	s_nop 1
	s_cmp_gt_u32 s14, 63
	s_cbranch_scc1 .Lmy_prep_done
	s_waitcnt vmcnt(4)
	s_cmp_lt_u32 s14, 16
	s_cselect_b32 s10, 32, 0
	v_cmp_gt_u32_e32 vcc, s10, v51
	v_cndmask_b32_e32 v76, 0, v76, vcc
	v_cndmask_b32_e32 v77, 0, v77, vcc
	v_cndmask_b32_e32 v78, 0, v78, vcc
	v_cndmask_b32_e32 v79, 0, v79, vcc
	v_cndmask_b32_e32 v80, 0, v80, vcc
	v_cndmask_b32_e32 v81, 0, v81, vcc
	v_cndmask_b32_e32 v82, 0, v82, vcc
	v_cndmask_b32_e32 v83, 0, v83, vcc
	ds_write_b128 v53, v[76:79] offset:34816
	ds_write_b128 v53, v[80:83] offset:43520
	s_waitcnt lgkmcnt(0)
	s_barrier
	ds_read_b32 v96, v54 offset:34816
	ds_read_b32 v97, v54 offset:35088
	ds_read_b32 v98, v54 offset:35360
	ds_read_b32 v99, v54 offset:35632
	ds_read_b32 v100, v54 offset:35904
	ds_read_b32 v101, v54 offset:36176
	ds_read_b32 v102, v54 offset:36448
	ds_read_b32 v103, v54 offset:36720
	s_waitcnt lgkmcnt(0)
	v_cvt_pk_bf16_f32 v104, v96, v97
	v_cvt_pk_bf16_f32 v105, v98, v99
	v_cvt_pk_bf16_f32 v106, v100, v101
	v_cvt_pk_bf16_f32 v107, v102, v103
	s_add_u32 s10, s12, 0x1400000
	s_addc_u32 s11, s13, 0
	global_store_dwordx4 v55, v[104:107], s[10:11]
	s_nop 1
; __device__ __forceinline__ float siluf(float x){ return x/(1.f+__expf(-x)); }
; __device__ __forceinline__ void phase_prep(KP kp_){ asm volatile("" : "+s"(kp_)); const Params p=load_params(kp_);
;     ...
;   float* modv=(float*)(ws+OFF_MOD);
;   for (int it=blockIdx.x; it<256; it+=gridDim.x){
;     float acc[3][12];
;     for(int a=0;a<3;++a)for(int j=0;j<12;++j)acc[a][j]=0.f;
;     for (int r=0;r<2;++r){ int k=tid+512*r;
;       float s0=siluf(p.c[k]), s1=siluf(p.c[1024+k]), s2=siluf(p.c_ctx[k]);
;       const float4* wp=(const float4*)(p.w_mod+(size_t)k*3072+it*12);
.Lmy_prep_done:
	s_waitcnt vmcnt(0)
	s_barrier
.LBB0_13:
	s_andn2_b64 vcc, exec, s[56:57]
	s_cbranch_vccnz .LBB0_90
	v_cmp_lt_i32_e32 vcc, v43, v42
	v_ashrrev_i32_e32 v1, 6, v8
	s_movk_i32 s10, 0x90
	v_cndmask_b32_e32 v2, v41, v43, vcc
	v_cmp_lt_i32_e32 vcc, v44, v42
	v_lshlrev_b32_e32 v24, 2, v2
	v_and_b32_e32 v0, 63, v8
	v_cndmask_b32_e32 v2, v41, v44, vcc
	v_cmp_lt_i32_e32 vcc, v45, v42
	v_lshlrev_b32_e32 v49, 2, v2
	v_cmp_eq_u32_e64 s[42:43], 0, v0
	v_cndmask_b32_e32 v2, v41, v45, vcc
	v_cmp_lt_i32_e32 vcc, v46, v42
	v_lshlrev_b32_e32 v50, 2, v2
	v_ashrrev_i32_e32 v9, 31, v8
	v_cndmask_b32_e32 v2, v41, v46, vcc
	v_cmp_lt_i32_e32 vcc, v47, v42
	v_lshlrev_b32_e32 v51, 2, v2
	s_waitcnt lgkmcnt(0)
	s_add_u32 s8, s8, 0x3b80000
	v_cndmask_b32_e32 v2, v41, v47, vcc
	v_cmp_lt_i32_e32 vcc, v48, v42
	v_lshlrev_b32_e32 v52, 2, v2
	v_readlane_b32 s12, v253, 6
	v_cndmask_b32_e32 v2, v41, v48, vcc
	v_lshlrev_b32_e32 v53, 2, v2
	v_mul_lo_u32 v2, v1, s10
	s_mov_b32 s10, 0x2aaaaaab
	v_mul_hi_i32 v0, v8, s10
	v_lshrrev_b32_e32 v1, 31, v0
	v_ashrrev_i32_e32 v0, 1, v0
	v_add_u32_e32 v3, v0, v1
	v_mul_lo_u32 v0, v3, 12
	v_sub_u32_e32 v55, v8, v0
	v_lshlrev_b64 v[0:1], 2, v[8:9]
	v_lshl_add_u64 v[26:27], s[46:47], 0, v[0:1]
	s_mov_b64 s[10:11], 0x1000
	v_lshl_add_u64 v[28:29], v[26:27], 0, s[10:11]
	v_mad_i64_i32 v[32:33], s[10:11], v8, s22, 0
	s_mov_b64 s[10:11], 0x1800
	s_nop 0
	v_lshl_add_u64 v[34:35], v[26:27], 0, s[10:11]
	v_mad_i64_i32 v[36:37], s[10:11], v12, s22, 0
	s_movk_i32 s10, 0xbf4
	s_nop 0
	v_mad_u64_u32 v[38:39], s[10:11], v3, s10, v[8:9]
	s_addc_u32 s9, s9, 0
	v_cmp_gt_i32_e64 s[44:45], 36, v8
	v_lshl_add_u32 v54, v8, 2, 0
	v_lshl_add_u64 v[30:31], s[48:49], 0, v[0:1]
	v_add_u32_e32 v39, 0, v2
	s_mul_i32 s48, s12, 12
	s_branch .LBB0_16
